# P6 (causal conv + SiLU) main loop: every packed f32 multiply whose two products feed one f32 add each fused into v_fma_f32 (56 packed multiplies removed; f32, single rounding)
# baseline (speedup 1.0000x reference)
; __device__ __forceinline__ float silu_f(float x) { return x * __builtin_amdgcn_rcpf(1.0f + __builtin_amdgcn_exp2f(-1.4426950408889634f * x)); }
; __device__ __forceinline__ float bflo(unsigned x) { return __uint_as_float(x << 16); }
; __device__ __forceinline__ float bfhi(unsigned x) { return __uint_as_float(x & 0xffff0000u); }
; __device__ __forceinline__ unsigned pk2(float lo, float hi) { return pg8::cvt_pk_bf16(lo, hi); }
; __device__ __forceinline__ float silu_f(float x) { return x * __builtin_amdgcn_rcpf(1.0f + __builtin_amdgcn_exp2f(-1.4426950408889634f * x)); }
; __device__ __forceinline__ void ph_conv(const bf16* XBC, const float* state_conv, const float* conv_w, const float* conv_b, bf16* XT, bf16* BN, bf16* CN, bf16* BT, int c_lo, int c_hi, int vcu, int G, int tid) {
;     ...
;         for (int t8 = 0; t8 < 2; ++t8) {
;             float y0[8], y1[8];
; #pragma unroll
;             for (int i = 0; i < 8; ++i) { const float x0 = bflo(raw[3 + t8 * 8 + i]), x1 = bfhi(raw[3 + t8 * 8 + i]);
;                 const float a0 = b0 + w0[0] * p0[0] + w0[1] * p0[1] + w0[2] * p0[2] + w0[3] * x0, a1 = b1 + w1[0] * p1[0] + w1[1] * p1[1] + w1[2] * p1[2] + w1[3] * x1;
;                 y0[i] = silu_f(a0); y1[i] = silu_f(a1); p0[0] = p0[1]; p0[1] = p0[2]; p0[2] = x0; p1[0] = p1[1]; p1[1] = p1[2]; p1[2] = x1; }
;             v4u t0, t1; t0.x = pk2(y0[0], y0[1]); t0.y = pk2(y0[2], y0[3]); t0.z = pk2(y0[4], y0[5]); t0.w = pk2(y0[6], y0[7]);
;             t1.x = pk2(y1[0], y1[1]); t1.y = pk2(y1[2], y1[3]); t1.z = pk2(y1[4], y1[5]); t1.w = pk2(y1[6], y1[7]);
.LBB0_837:
	v_lshlrev_b32_e32 v82, 16, v4
	v_fma_f32 v0, v14, v0, v18
	v_mov_b32_e32 v83, v5
	v_fma_f32 v0, v15, v1, v0
	v_and_b32_e32 v84, 0xffff0000, v4
	v_fma_f32 v0, v11, v83, v0
	v_fma_f32 v0, v10, v82, v0
	v_mov_b32_e32 v85, v3
	v_fma_f32 v2, v38, v6, v19
	v_fma_f32 v2, v39, v7, v2
	v_lshl_add_u32 v40, s21, 1, v52
	v_fma_f32 v2, v35, v85, v2
	v_fma_f32 v6, v34, v84, v2
	v_mul_f32_e32 v2, 0xbfb8aa3b, v0
	v_exp_f32_e32 v2, v2
	v_mul_f32_e32 v4, 0xbfb8aa3b, v6
	v_exp_f32_e32 v4, v4
	v_ashrrev_i32_e32 v41, 31, v40
	v_add_f32_e32 v2, 1.0, v2
	v_rcp_f32_e32 v49, v2
	v_add_f32_e32 v2, 1.0, v4
	v_rcp_f32_e32 v51, v2
	v_mov_b32_e32 v4, v1
	v_mov_b32_e32 v2, v7
	v_fma_f32 v4, v14, v4, v18
	v_fma_f32 v81, v15, v5, v4
	v_lshlrev_b32_e32 v5, 16, v48
	v_mul_f32_e32 v51, v6, v51
	v_mov_b32_e32 v6, v5
	v_mov_b32_e32 v7, v82
	v_mul_f32_e32 v50, v0, v49
	v_and_b32_e32 v1, 0xffff0000, v48
	v_and_b32_e32 v0, 0xffff0000, v43
	v_fma_f32 v2, v38, v2, v19
	v_lshlrev_b32_e32 v4, 16, v43
	v_fma_f32 v43, v11, v7, v81
	v_fma_f32 v86, v39, v3, v2
	v_fma_f32 v43, v10, v6, v43
	v_fma_f32 v3, v37, v83, v18
	v_mul_f32_e32 v48, 0xbfb8aa3b, v43
	v_fma_f32 v83, v36, v82, v3
	v_exp_f32_e32 v81, v48
	v_fma_f32 v49, v11, v5, v83
	v_fma_f32 v48, v10, v4, v49
	v_mul_f32_e32 v49, 0xbfb8aa3b, v48
	v_exp_f32_e32 v49, v49
	v_fma_f32 v3, v33, v85, v19
	v_fma_f32 v83, v32, v84, v3
	v_add_f32_e32 v2, 1.0, v81
	v_rcp_f32_e32 v81, v2
	v_add_f32_e32 v2, 1.0, v49
	v_rcp_f32_e32 v49, v2
	v_mul_f32_e32 v82, v43, v81
	v_fma_f32 v7, v37, v7, v18
	v_fma_f32 v85, v36, v6, v7
	v_mov_b32_e32 v6, v1
	v_mov_b32_e32 v7, v84
	v_mul_f32_e32 v81, v48, v49
	v_pk_mul_f32 v[48:49], v[34:35], v[6:7]
	v_add_f32_e32 v43, v49, v86
	v_add_f32_e32 v43, v48, v43
	v_mul_f32_e32 v48, 0xbfb8aa3b, v43
	v_exp_f32_e32 v84, v48
	v_fma_f32 v7, v33, v7, v19
	v_fma_f32 v49, v35, v1, v83
	v_fma_f32 v83, v34, v0, v49
	v_mul_f32_e32 v48, 0xbfb8aa3b, v83
	v_exp_f32_e32 v86, v48
	v_fma_f32 v89, v32, v6, v7
	v_add_f32_e32 v84, 1.0, v84
	v_add_f32_e32 v86, 1.0, v86
	v_fma_f32 v7, v33, v1, v19
	v_rcp_f32_e32 v84, v84
	v_rcp_f32_e32 v87, v86
	v_fma_f32 v49, v37, v5, v18
	v_fma_f32 v90, v32, v0, v7
	v_lshlrev_b32_e32 v7, 16, v42
	v_fma_f32 v88, v36, v4, v49
	v_mov_b32_e32 v48, v4
	v_mov_b32_e32 v49, v7
	v_mul_f32_e32 v86, v43, v84
	v_fma_f32 v6, v12, v48, v85
	v_mul_f32_e32 v84, v83, v87
	v_fma_f32 v83, v13, v49, v6
	v_mul_f32_e32 v6, 0xbfb8aa3b, v83
	v_exp_f32_e32 v48, v6
	v_lshlrev_b32_e32 v6, 16, v47
	v_and_b32_e32 v2, 0xffff0000, v47
	v_pk_mov_b32 v[4:5], v[6:7], v[4:5] op_sel:[1,0]
	v_add_f32_e32 v47, 1.0, v48
	v_fma_f32 v49, v11, v7, v88
	v_fma_f32 v48, v10, v6, v49
	v_mul_f32_e32 v49, 0xbfb8aa3b, v48
	v_and_b32_e32 v43, 0xffff0000, v45
	v_lshlrev_b32_e32 v45, 16, v45
	v_exp_f32_e32 v49, v49
	v_fma_f32 v5, v37, v5, v18
	v_fma_f32 v85, v36, v4, v5
	v_mov_b32_e32 v4, v6
	v_mov_b32_e32 v5, v45
	v_add_f32_e32 v49, 1.0, v49
	v_fma_f32 v4, v12, v4, v85
	v_fma_f32 v4, v13, v5, v4
	v_mul_f32_e32 v5, 0xbfb8aa3b, v4
	v_rcp_f32_e32 v49, v49
	v_exp_f32_e32 v5, v5
	v_and_b32_e32 v3, 0xffff0000, v42
	v_rcp_f32_e32 v47, v47
	v_mul_f32_e32 v85, v48, v49
	v_mov_b32_e32 v48, v0
	v_mov_b32_e32 v49, v3
	v_add_f32_e32 v5, 1.0, v5
	v_rcp_f32_e32 v5, v5
	v_fma_f32 v48, v30, v48, v89
	v_fma_f32 v88, v31, v49, v48
	v_mul_f32_e32 v48, 0xbfb8aa3b, v88
	v_exp_f32_e32 v89, v48
	v_mul_f32_e32 v87, v83, v47
	v_mul_f32_e32 v83, v4, v5
	v_pk_mov_b32 v[0:1], v[2:3], v[0:1] op_sel:[1,0]
	v_and_b32_e32 v42, 0xffff0000, v44
	v_lshlrev_b32_e32 v44, 16, v44
	v_fma_f32 v5, v37, v7, v18
	v_fma_f32 v47, v36, v6, v5
	v_fma_f32 v1, v33, v1, v19
	v_fma_f32 v5, v11, v45, v47
	v_add_f32_e32 v47, 1.0, v89
	v_fma_f32 v89, v32, v0, v1
	v_mov_b32_e32 v0, v2
	v_mov_b32_e32 v1, v43
	v_fma_f32 v0, v30, v0, v89
	v_fma_f32 v49, v35, v3, v90
	v_fma_f32 v90, v31, v1, v0
	v_mul_f32_e32 v0, 0xbfb8aa3b, v90
	v_exp_f32_e32 v0, v0
	v_rcp_f32_e32 v47, v47
	v_fma_f32 v4, v10, v44, v5
	v_fma_f32 v48, v34, v2, v49
	v_add_f32_e32 v0, 1.0, v0
	v_rcp_f32_e32 v5, v0
	v_mul_f32_e32 v49, 0xbfb8aa3b, v48
	v_fma_f32 v1, v33, v3, v19
	v_mul_f32_e32 v92, v88, v47
	v_fma_f32 v47, v32, v2, v1
	v_exp_f32_e32 v49, v49
	v_fma_f32 v1, v35, v43, v47
	v_fma_f32 v91, v34, v42, v1
	v_mul_f32_e32 v0, 0xbfb8aa3b, v4
	v_exp_f32_e32 v0, v0
	v_mul_f32_e32 v1, 0xbfb8aa3b, v91
	v_exp_f32_e32 v1, v1
	v_add_f32_e32 v49, 1.0, v49
	v_rcp_f32_e32 v49, v49
	v_add_f32_e32 v0, 1.0, v0
	v_mul_f32_e32 v88, v90, v5
	v_rcp_f32_e32 v5, v0
	v_add_f32_e32 v90, 1.0, v1
	v_pk_mov_b32 v[0:1], v[44:45], v[6:7] op_sel:[1,0]
	v_mul_f32_e32 v89, v48, v49
	v_lshlrev_b32_e32 v49, 16, v46
	v_fma_f32 v1, v37, v1, v18
	v_mov_b32_e32 v48, v44
	v_fma_f32 v6, v36, v0, v1
	v_and_b32_e32 v47, 0xffff0000, v46
	v_fma_f32 v0, v12, v48, v6
	v_fma_f32 v6, v13, v49, v0
	v_pk_mov_b32 v[0:1], v[42:43], v[2:3] op_sel:[1,0]
	v_mov_b32_e32 v46, v42
	v_rcp_f32_e32 v3, v90
	v_fma_f32 v1, v33, v1, v19
	v_fma_f32 v2, v32, v0, v1
	s_lshl_b32 s4, s21, 6
	v_fma_f32 v0, v30, v46, v2
	v_fma_f32 v0, v31, v47, v0
	v_mul_f32_e32 v1, 0xbfb8aa3b, v6
	v_mul_f32_e32 v2, 0xbfb8aa3b, v0
	v_exp_f32_e32 v1, v1
	v_exp_f32_e32 v2, v2
	s_lshl_b32 s20, s12, 4
	v_lshlrev_b64 v[40:41], 14, v[40:41]
	v_add_f32_e32 v1, 1.0, v1
	v_add_f32_e32 v2, 1.0, v2
	v_rcp_f32_e32 v1, v1
	v_rcp_f32_e32 v2, v2
	s_or_b32 s10, s4, s20
	v_lshl_add_u64 v[40:41], v[26:27], 0, v[40:41]
	v_mul_f32_e32 v90, v4, v5
	v_mul_f32_e32 v91, v91, v3
	v_mul_f32_e32 v46, v6, v1
	v_mul_f32_e32 v48, v0, v2
	v_cvt_pk_bf16_f32 v0, v50, v82
	v_cvt_pk_bf16_f32 v1, v81, v87
	v_cvt_pk_bf16_f32 v2, v85, v83
	v_cvt_pk_bf16_f32 v3, v90, v46
	v_cvt_pk_bf16_f32 v4, v51, v86
	v_cvt_pk_bf16_f32 v5, v84, v92
	v_cvt_pk_bf16_f32 v6, v89, v88
	v_cvt_pk_bf16_f32 v7, v91, v48
	s_and_saveexec_b64 s[12:13], s[0:1]
	s_xor_b64 s[12:13], exec, s[12:13]
	s_cbranch_execz .LBB0_843
; __device__ __forceinline__ unsigned pk2(float lo, float hi) { return pg8::cvt_pk_bf16(lo, hi); }
; __device__ __forceinline__ void ph_conv(const bf16* XBC, const float* state_conv, const float* conv_w, const float* conv_b, bf16* XT, bf16* BN, bf16* CN, bf16* BT, int c_lo, int c_hi, int vcu, int G, int tid) {
;     ...
;             else { const int cc = ch - 768;
; #pragma unroll
;                 for (int i = 0; i < 8; ++i) *(unsigned*)(CN + (size_t)(row0 + t8 * 8 + i) * 256 + cc) = pk2(y0[i], y1[i]); }
	s_ashr_i32 s11, s10, 31
	s_lshl_b64 s[14:15], s[10:11], 9
	s_and_saveexec_b64 s[16:17], s[2:3]
	s_xor_b64 s[16:17], exec, s[16:17]
	s_cbranch_execz .LBB0_840
	s_or_b32 s24, s10, 1
	s_ashr_i32 s25, s24, 31
	v_lshl_add_u64 v[0:1], v[22:23], 0, s[14:15]
	s_lshl_b64 s[24:25], s[24:25], 9
	v_cvt_pk_bf16_f32 v2, v50, v51
	global_store_dword v[0:1], v2, off offset:-1536
	v_lshl_add_u64 v[0:1], v[22:23], 0, s[24:25]
	s_or_b32 s24, s10, 2
	s_ashr_i32 s25, s24, 31
	s_lshl_b64 s[24:25], s[24:25], 9
	v_cvt_pk_bf16_f32 v2, v82, v86
	global_store_dword v[0:1], v2, off offset:-1536
	v_lshl_add_u64 v[0:1], v[22:23], 0, s[24:25]
	s_or_b32 s24, s10, 3
	s_ashr_i32 s25, s24, 31
	s_lshl_b64 s[24:25], s[24:25], 9
	v_cvt_pk_bf16_f32 v2, v81, v84
	global_store_dword v[0:1], v2, off offset:-1536
	v_lshl_add_u64 v[0:1], v[22:23], 0, s[24:25]
	s_or_b32 s24, s10, 4
	s_ashr_i32 s25, s24, 31
	s_lshl_b64 s[24:25], s[24:25], 9
	v_cvt_pk_bf16_f32 v2, v87, v92
	global_store_dword v[0:1], v2, off offset:-1536
	v_lshl_add_u64 v[0:1], v[22:23], 0, s[24:25]
	s_or_b32 s24, s10, 5
	s_ashr_i32 s25, s24, 31
	s_lshl_b64 s[24:25], s[24:25], 9
	v_cvt_pk_bf16_f32 v2, v85, v89
	global_store_dword v[0:1], v2, off offset:-1536
	v_lshl_add_u64 v[0:1], v[22:23], 0, s[24:25]
	s_or_b32 s24, s10, 6
	s_ashr_i32 s25, s24, 31
	s_lshl_b64 s[24:25], s[24:25], 9
	v_cvt_pk_bf16_f32 v2, v83, v88
	global_store_dword v[0:1], v2, off offset:-1536
	v_lshl_add_u64 v[0:1], v[22:23], 0, s[24:25]
	s_or_b32 s24, s10, 7
	s_ashr_i32 s25, s24, 31
	v_cvt_pk_bf16_f32 v2, v90, v91
	s_lshl_b64 s[24:25], s[24:25], 9
	global_store_dword v[0:1], v2, off offset:-1536
	v_cvt_pk_bf16_f32 v2, v46, v48
	v_lshl_add_u64 v[0:1], v[22:23], 0, s[24:25]
	global_store_dword v[0:1], v2, off offset:-1536

; __device__ __forceinline__ float silu_f(float x) { return x * __builtin_amdgcn_rcpf(1.0f + __builtin_amdgcn_exp2f(-1.4426950408889634f * x)); }
; __device__ __forceinline__ float bflo(unsigned x) { return __uint_as_float(x << 16); }
; __device__ __forceinline__ float bfhi(unsigned x) { return __uint_as_float(x & 0xffff0000u); }
; __device__ __forceinline__ unsigned pk2(float lo, float hi) { return pg8::cvt_pk_bf16(lo, hi); }
; __device__ __forceinline__ float silu_f(float x) { return x * __builtin_amdgcn_rcpf(1.0f + __builtin_amdgcn_exp2f(-1.4426950408889634f * x)); }
; __device__ __forceinline__ void ph_conv(const bf16* XBC, const float* state_conv, const float* conv_w, const float* conv_b, bf16* XT, bf16* BN, bf16* CN, bf16* BT, int c_lo, int c_hi, int vcu, int G, int tid) {
;     ...
;         for (int t8 = 0; t8 < 2; ++t8) {
;             float y0[8], y1[8];
; #pragma unroll
;             for (int i = 0; i < 8; ++i) { const float x0 = bflo(raw[3 + t8 * 8 + i]), x1 = bfhi(raw[3 + t8 * 8 + i]);
;                 const float a0 = b0 + w0[0] * p0[0] + w0[1] * p0[1] + w0[2] * p0[2] + w0[3] * x0, a1 = b1 + w1[0] * p1[0] + w1[1] * p1[1] + w1[2] * p1[2] + w1[3] * x1;
;                 y0[i] = silu_f(a0); y1[i] = silu_f(a1); p0[0] = p0[1]; p0[1] = p0[2]; p0[2] = x0; p1[0] = p1[1]; p1[1] = p1[2]; p1[2] = x1; }
;             v4u t0, t1; t0.x = pk2(y0[0], y0[1]); t0.y = pk2(y0[2], y0[3]); t0.z = pk2(y0[4], y0[5]); t0.w = pk2(y0[6], y0[7]);
;             t1.x = pk2(y1[0], y1[1]); t1.y = pk2(y1[2], y1[3]); t1.z = pk2(y1[4], y1[5]); t1.w = pk2(y1[6], y1[7]);
.LBB0_845:
	s_or_b64 exec, exec, s[12:13]
	s_nop 0
	v_lshlrev_b32_e32 v1, 16, v80
	v_fma_f32 v0, v37, v45, v18
	v_fma_f32 v2, v36, v44, v0
	v_mov_b32_e32 v0, v49
	v_and_b32_e32 v3, 0xffff0000, v80
	v_fma_f32 v0, v12, v0, v2
	v_fma_f32 v0, v13, v1, v0
	v_mov_b32_e32 v7, v44
	v_fma_f32 v2, v33, v43, v19
	v_fma_f32 v6, v32, v42, v2
	v_mov_b32_e32 v2, v47
	v_mov_b32_e32 v48, v1
	v_fma_f32 v2, v30, v2, v6
	v_mul_f32_e32 v4, 0xbfb8aa3b, v0
	v_exp_f32_e32 v4, v4
	v_fma_f32 v2, v31, v3, v2
	v_mul_f32_e32 v5, 0xbfb8aa3b, v2
	v_exp_f32_e32 v5, v5
	v_add_f32_e32 v4, 1.0, v4
	v_rcp_f32_e32 v4, v4
	v_mov_b32_e32 v6, v49
	v_add_f32_e32 v5, 1.0, v5
	v_rcp_f32_e32 v5, v5
	v_mul_f32_e32 v43, v0, v4
	v_fma_f32 v0, v37, v7, v18
	v_fma_f32 v0, v36, v6, v0
	v_mov_b32_e32 v6, v47
	v_mov_b32_e32 v7, v42
	v_mul_f32_e32 v45, v2, v5
	v_fma_f32 v2, v33, v7, v19
	v_fma_f32 v2, v32, v6, v2
	v_mov_b32_e32 v46, v3
	v_fma_f32 v7, v37, v49, v18
	v_lshlrev_b32_e32 v49, 16, v79
	v_fma_f32 v42, v36, v48, v7
	v_pk_mul_f32 v[6:7], v[32:33], v[46:47]
	v_mov_b32_e32 v46, v1
	v_mov_b32_e32 v47, v49
	v_lshlrev_b32_e32 v48, 16, v78
	v_fma_f32 v0, v12, v46, v0
	v_fma_f32 v0, v13, v47, v0
	v_mul_f32_e32 v44, 0xbfb8aa3b, v0
	v_exp_f32_e32 v44, v44
	v_add_f32_e32 v7, v19, v7
	v_and_b32_e32 v5, 0xffff0000, v79
	v_fma_f32 v42, v11, v49, v42
	v_add_f32_e32 v47, v6, v7
	v_add_f32_e32 v6, 1.0, v44
	v_rcp_f32_e32 v44, v6
	v_fma_f32 v42, v10, v48, v42
	v_mul_f32_e32 v46, 0xbfb8aa3b, v42
	v_exp_f32_e32 v46, v46
	v_mul_f32_e32 v44, v0, v44
	v_mov_b32_e32 v0, v49
	v_add_f32_e32 v6, 1.0, v46
	v_fma_f32 v1, v37, v1, v18
	v_fma_f32 v79, v36, v0, v1
	v_mov_b32_e32 v0, v3
	v_mov_b32_e32 v1, v5
	v_rcp_f32_e32 v46, v6
	v_and_b32_e32 v4, 0xffff0000, v78
	v_fma_f32 v0, v30, v0, v2
	v_fma_f32 v2, v31, v1, v0
	v_mul_f32_e32 v0, 0xbfb8aa3b, v2
	v_mul_f32_e32 v42, v42, v46
	v_exp_f32_e32 v46, v0
	v_and_b32_e32 v7, 0xffff0000, v77
	v_fma_f32 v1, v35, v5, v47
	v_fma_f32 v47, v34, v4, v1
	v_mul_f32_e32 v0, 0xbfb8aa3b, v47
	v_exp_f32_e32 v78, v0
	v_add_f32_e32 v46, 1.0, v46
	v_rcp_f32_e32 v46, v46
	v_add_f32_e32 v78, 1.0, v78
	v_rcp_f32_e32 v80, v78
	v_fma_f32 v1, v37, v49, v18
	v_mul_f32_e32 v78, v2, v46
	v_mov_b32_e32 v2, v5
	v_fma_f32 v82, v36, v48, v1
	v_pk_mul_f32 v[0:1], v[32:33], v[2:3]
	v_lshlrev_b32_e32 v3, 16, v77
	v_mul_f32_e32 v46, v47, v80
	v_mov_b32_e32 v80, v48
	v_mov_b32_e32 v81, v3
	v_add_f32_e32 v1, v19, v1
	v_fma_f32 v2, v12, v80, v79
	v_fma_f32 v47, v13, v81, v2
	v_mul_f32_e32 v2, 0xbfb8aa3b, v47
	v_exp_f32_e32 v77, v2
	v_add_f32_e32 v83, v0, v1
	v_lshlrev_b32_e32 v2, 16, v76
	v_fma_f32 v1, v33, v5, v19
	v_fma_f32 v79, v32, v4, v1
	v_add_f32_e32 v0, 1.0, v77
	v_and_b32_e32 v6, 0xffff0000, v76
	v_rcp_f32_e32 v76, v0
	v_pk_mov_b32 v[48:49], v[2:3], v[48:49] op_sel:[1,0]
	v_fma_f32 v1, v11, v3, v82
	v_fma_f32 v81, v10, v2, v1
	v_mul_f32_e32 v0, 0xbfb8aa3b, v81
	v_exp_f32_e32 v77, v0
	v_mul_f32_e32 v47, v47, v76
	v_lshlrev_b32_e32 v80, 16, v75
	v_add_f32_e32 v76, 1.0, v77
	v_rcp_f32_e32 v82, v76
	v_fma_f32 v49, v37, v49, v18
	v_pk_mul_f32 v[76:77], v[36:37], v[2:3]
	v_mov_b32_e32 v3, v80
	v_fma_f32 v84, v36, v48, v49
	v_pk_mul_f32 v[48:49], v[12:13], v[2:3]
	v_and_b32_e32 v0, 0xffff0000, v75
	v_add_f32_e32 v3, v48, v84
	v_add_f32_e32 v3, v3, v49
	v_mul_f32_e32 v48, 0xbfb8aa3b, v3
	v_add_f32_e32 v75, v18, v77
	v_exp_f32_e32 v48, v48
	v_mul_f32_e32 v49, v81, v82
	v_add_f32_e32 v82, v76, v75
	v_mov_b32_e32 v76, v4
	v_mov_b32_e32 v77, v7
	v_add_f32_e32 v48, 1.0, v48
	v_fma_f32 v75, v30, v76, v83
	v_fma_f32 v83, v31, v77, v75
	v_mul_f32_e32 v75, 0xbfb8aa3b, v83
	v_rcp_f32_e32 v48, v48
	v_exp_f32_e32 v76, v75
	v_lshlrev_b32_e32 v81, 16, v74
	v_pk_mov_b32 v[4:5], v[6:7], v[4:5] op_sel:[1,0]
	v_mul_f32_e32 v48, v3, v48
	v_add_f32_e32 v3, 1.0, v76
	v_rcp_f32_e32 v3, v3
	v_fma_f32 v77, v35, v7, v79
	v_fma_f32 v79, v34, v6, v77
	v_mul_f32_e32 v76, 0xbfb8aa3b, v79
	v_exp_f32_e32 v76, v76
	v_and_b32_e32 v1, 0xffff0000, v74
	v_fma_f32 v74, v12, v80, v82
	v_fma_f32 v5, v33, v5, v19
	v_fma_f32 v84, v13, v81, v74
	v_fma_f32 v74, v32, v4, v5
	v_pk_mul_f32 v[4:5], v[32:33], v[6:7]
	v_mov_b32_e32 v7, v0
	v_mul_f32_e32 v75, v83, v3
	v_add_f32_e32 v3, 1.0, v76
	v_pk_mul_f32 v[76:77], v[30:31], v[6:7]
	v_rcp_f32_e32 v3, v3
	v_add_f32_e32 v7, v76, v74
	v_add_f32_e32 v7, v7, v77
	v_mul_f32_e32 v74, 0xbfb8aa3b, v7
	v_exp_f32_e32 v74, v74
	v_mul_f32_e32 v77, v79, v3
	v_add_f32_e32 v3, v19, v5
	v_add_f32_e32 v3, v4, v3
	v_add_f32_e32 v4, 1.0, v74
	v_rcp_f32_e32 v74, v4
	v_mov_b32_e32 v82, v80
	v_fma_f32 v3, v30, v0, v3
	v_fma_f32 v76, v31, v1, v3
	v_mul_f32_e32 v3, 0xbfb8aa3b, v84
	v_exp_f32_e32 v3, v3
	v_mul_f32_e32 v4, 0xbfb8aa3b, v76
	v_exp_f32_e32 v4, v4
	v_mov_b32_e32 v83, v2
	v_pk_mul_f32 v[82:83], v[36:37], v[82:83]
	v_add_f32_e32 v3, 1.0, v3
	v_add_f32_e32 v2, v18, v83
	v_mul_f32_e32 v74, v7, v74
	v_rcp_f32_e32 v7, v3
	v_add_f32_e32 v79, 1.0, v4
	v_lshlrev_b32_e32 v3, 16, v73
	v_add_f32_e32 v4, v82, v2
	v_mov_b32_e32 v2, v81
	v_and_b32_e32 v5, 0xffff0000, v73
	v_fma_f32 v2, v12, v2, v4
	v_fma_f32 v73, v13, v3, v2
	v_mov_b32_e32 v2, v0
	v_mov_b32_e32 v3, v6
	v_mov_b32_e32 v4, v1
	v_fma_f32 v0, v33, v3, v19
	v_fma_f32 v2, v32, v2, v0
	v_rcp_f32_e32 v3, v79
	v_fma_f32 v0, v30, v4, v2
	v_fma_f32 v0, v31, v5, v0
	v_mul_f32_e32 v1, 0xbfb8aa3b, v73
	v_mul_f32_e32 v2, 0xbfb8aa3b, v0
	v_exp_f32_e32 v1, v1
	v_exp_f32_e32 v2, v2
	v_mul_f32_e32 v79, v84, v7
	v_mul_f32_e32 v80, v76, v3
	v_add_f32_e32 v1, 1.0, v1
	v_add_f32_e32 v2, 1.0, v2
	v_rcp_f32_e32 v1, v1
	v_rcp_f32_e32 v2, v2
	v_mul_f32_e32 v73, v73, v1
	v_mul_f32_e32 v76, v0, v2
	v_cvt_pk_bf16_f32 v0, v43, v44
	v_cvt_pk_bf16_f32 v1, v42, v47
	v_cvt_pk_bf16_f32 v2, v49, v48
	v_cvt_pk_bf16_f32 v3, v79, v73
	v_cvt_pk_bf16_f32 v4, v45, v78
	v_cvt_pk_bf16_f32 v5, v46, v75
	v_cvt_pk_bf16_f32 v6, v77, v74
	v_cvt_pk_bf16_f32 v7, v80, v76
	s_and_saveexec_b64 s[12:13], s[0:1]
	s_xor_b64 s[12:13], exec, s[12:13]
	s_cbranch_execz .LBB0_851
; __device__ __forceinline__ unsigned pk2(float lo, float hi) { return pg8::cvt_pk_bf16(lo, hi); }
; __device__ __forceinline__ void ph_conv(const bf16* XBC, const float* state_conv, const float* conv_w, const float* conv_b, bf16* XT, bf16* BN, bf16* CN, bf16* BT, int c_lo, int c_hi, int vcu, int G, int tid) {
;     ...
;             else if (tid < 384) { const int cb = ch - 512, g = cb >> 7, n = cb & 127;
; #pragma unroll
;                 for (int i = 0; i < 8; ++i) *(unsigned*)(BN + (size_t)(row0 + t8 * 8 + i) * 256 + cb) = pk2(y0[i], y1[i]);
;                 bf16* d = BT + ((size_t)(ci * 2 + g) * 128 + n) * 64 + tl; *(v4u*)d = t0; *(v4u*)(d + 64) = t1; }
;             else { const int cc = ch - 768;
; #pragma unroll
;                 for (int i = 0; i < 8; ++i) *(unsigned*)(CN + (size_t)(row0 + t8 * 8 + i) * 256 + cc) = pk2(y0[i], y1[i]); }
	s_or_b32 s14, s10, 8
	s_ashr_i32 s15, s14, 31
	s_lshl_b64 s[14:15], s[14:15], 9
	s_and_saveexec_b64 s[16:17], s[2:3]
	s_xor_b64 s[16:17], exec, s[16:17]
	s_cbranch_execz .LBB0_848
	s_or_b32 s24, s10, 9
	s_ashr_i32 s25, s24, 31
	v_lshl_add_u64 v[0:1], v[22:23], 0, s[14:15]
	s_lshl_b64 s[24:25], s[24:25], 9
	v_cvt_pk_bf16_f32 v2, v43, v45
	global_store_dword v[0:1], v2, off offset:-1536
	v_lshl_add_u64 v[0:1], v[22:23], 0, s[24:25]
	s_or_b32 s24, s10, 10
	s_ashr_i32 s25, s24, 31
	s_lshl_b64 s[24:25], s[24:25], 9
	v_cvt_pk_bf16_f32 v2, v44, v78
	global_store_dword v[0:1], v2, off offset:-1536
	v_lshl_add_u64 v[0:1], v[22:23], 0, s[24:25]
	s_or_b32 s24, s10, 11
	s_ashr_i32 s25, s24, 31
	s_lshl_b64 s[24:25], s[24:25], 9
	v_cvt_pk_bf16_f32 v2, v42, v46
	global_store_dword v[0:1], v2, off offset:-1536
	v_lshl_add_u64 v[0:1], v[22:23], 0, s[24:25]
	s_or_b32 s24, s10, 12
	s_ashr_i32 s25, s24, 31
	s_lshl_b64 s[24:25], s[24:25], 9
	v_cvt_pk_bf16_f32 v2, v47, v75
	global_store_dword v[0:1], v2, off offset:-1536
	v_lshl_add_u64 v[0:1], v[22:23], 0, s[24:25]
	s_or_b32 s24, s10, 13
	s_ashr_i32 s25, s24, 31
	s_lshl_b64 s[24:25], s[24:25], 9
	v_cvt_pk_bf16_f32 v2, v49, v77
	global_store_dword v[0:1], v2, off offset:-1536
	v_lshl_add_u64 v[0:1], v[22:23], 0, s[24:25]
	s_or_b32 s24, s10, 14
	s_ashr_i32 s25, s24, 31
	s_lshl_b64 s[24:25], s[24:25], 9
	v_cvt_pk_bf16_f32 v2, v48, v74
	global_store_dword v[0:1], v2, off offset:-1536
	v_lshl_add_u64 v[0:1], v[22:23], 0, s[24:25]
	s_or_b32 s24, s10, 15
	s_ashr_i32 s25, s24, 31
	v_cvt_pk_bf16_f32 v2, v79, v80
	s_lshl_b64 s[24:25], s[24:25], 9
	global_store_dword v[0:1], v2, off offset:-1536
	v_cvt_pk_bf16_f32 v2, v73, v76
	v_lshl_add_u64 v[0:1], v[22:23], 0, s[24:25]
	global_store_dword v[0:1], v2, off offset:-1536
